# attention tile loop: s_setprio 2 around the QK and PV MFMA runs, 0 across the softmax (GEMM-template style flips)
# speedup vs baseline: 1.0066x; 1.0034x over previous
.LBB0_554:
	s_or_b64 exec, exec, s[6:7]
	global_load_dwordx4 v[2:5], v[174:175], off
	s_add_i32 s7, s64, 3
	s_and_b32 s6, s7, 1
	s_cmp_gt_i32 s7, s26
	s_cbranch_scc1 .LBB0_558
	s_mul_i32 s7, s6, 0x3400
	v_add_u32_e32 v0, s7, v169
	ds_read_b128 v[6:9], v0
	ds_read_b128 v[10:13], v0 offset:32
	ds_read_b128 v[128:131], v0 offset:6656
	ds_read_b128 v[132:135], v0 offset:6688
	ds_read_b128 v[136:139], v0 offset:64
	ds_read_b128 v[140:143], v0 offset:96
	ds_read_b128 v[144:147], v0 offset:6720
	ds_read_b128 v[148:151], v0 offset:6752
	ds_read_b128 v[180:183], v0 offset:128
	ds_read_b128 v[184:187], v0 offset:160
	ds_read_b128 v[188:191], v0 offset:6784
	ds_read_b128 v[192:195], v0 offset:6816
	s_waitcnt lgkmcnt(8)
	s_setprio 2
	v_mfma_f32_32x32x16_bf16 v[80:95], v[6:9], v[116:119], v[48:63]
	v_mfma_f32_32x32x16_bf16 v[64:79], v[128:131], v[116:119], v[48:63]
	v_mfma_f32_32x32x16_bf16 v[80:95], v[10:13], v[112:115], v[80:95]
	v_mfma_f32_32x32x16_bf16 v[64:79], v[132:135], v[112:115], v[64:79]
	s_waitcnt lgkmcnt(4)
	v_mfma_f32_32x32x16_bf16 v[80:95], v[136:139], v[108:111], v[80:95]
	v_mfma_f32_32x32x16_bf16 v[64:79], v[144:147], v[108:111], v[64:79]
	v_mfma_f32_32x32x16_bf16 v[80:95], v[140:143], v[104:107], v[80:95]
	v_mfma_f32_32x32x16_bf16 v[64:79], v[148:151], v[104:107], v[64:79]
	s_waitcnt lgkmcnt(0)
	v_mfma_f32_32x32x16_bf16 v[80:95], v[180:183], v[120:123], v[80:95]
	v_mfma_f32_32x32x16_bf16 v[64:79], v[188:191], v[120:123], v[64:79]
	v_mfma_f32_32x32x16_bf16 v[80:95], v[184:187], v[124:127], v[80:95]
	v_mfma_f32_32x32x16_bf16 v[64:79], v[192:195], v[124:127], v[64:79]
	s_setprio 0
	s_mul_i32 s7, s6, 0x2200
	v_add_u32_e32 v6, s7, v241
	v_add_u32_e32 v0, s7, v242
	ds_read2_b64 v[148:151], v6 offset1:2
	ds_read2_b64 v[144:147], v6 offset0:4 offset1:6
	ds_read2_b64 v[140:143], v6 offset0:8 offset1:10
	ds_read2_b64 v[136:139], v6 offset0:12 offset1:14
	ds_read2_b64 v[132:135], v0 offset0:32 offset1:34
	ds_read2_b64 v[128:131], v0 offset0:36 offset1:38
	ds_read2_b64 v[10:13], v0 offset0:40 offset1:42
	ds_read2_b64 v[6:9], v0 offset0:44 offset1:46
.LBB0_557:
	v_exp_f32_e32 v196, v80
	v_exp_f32_e32 v212, v64
	v_exp_f32_e32 v197, v81
	v_exp_f32_e32 v213, v65
	v_exp_f32_e32 v198, v82
	v_exp_f32_e32 v214, v66
	v_add_f32_e32 v229, v212, v196
	v_exp_f32_e32 v199, v83
	v_exp_f32_e32 v215, v67
	v_add_f32_e32 v230, v213, v197
	v_add_f32_e32 v229, v230, v229
	v_exp_f32_e32 v200, v84
	v_exp_f32_e32 v216, v68
	v_add_f32_e32 v228, v214, v198
	v_add_f32_e32 v229, v228, v229
	v_exp_f32_e32 v201, v85
	v_exp_f32_e32 v217, v69
	v_add_f32_e32 v230, v215, v199
	v_add_f32_e32 v229, v230, v229
	v_exp_f32_e32 v202, v86
	v_exp_f32_e32 v218, v70
	v_add_f32_e32 v228, v216, v200
	v_add_f32_e32 v229, v228, v229
	v_exp_f32_e32 v203, v87
	v_exp_f32_e32 v219, v71
	v_add_f32_e32 v230, v217, v201
	v_add_f32_e32 v229, v230, v229
	v_exp_f32_e32 v204, v88
	v_exp_f32_e32 v220, v72
	v_add_f32_e32 v228, v218, v202
	v_add_f32_e32 v229, v228, v229
	v_exp_f32_e32 v205, v89
	v_exp_f32_e32 v221, v73
	v_add_f32_e32 v230, v219, v203
	v_add_f32_e32 v229, v230, v229
	v_exp_f32_e32 v206, v90
	v_exp_f32_e32 v222, v74
	v_add_f32_e32 v228, v220, v204
	v_add_f32_e32 v229, v228, v229
	v_exp_f32_e32 v207, v91
	v_exp_f32_e32 v223, v75
	v_add_f32_e32 v230, v221, v205
	v_add_f32_e32 v229, v230, v229
	v_exp_f32_e32 v208, v92
	v_exp_f32_e32 v224, v76
	v_add_f32_e32 v228, v222, v206
	v_add_f32_e32 v229, v228, v229
	v_exp_f32_e32 v209, v93
	v_exp_f32_e32 v225, v77
	v_add_f32_e32 v230, v223, v207
	v_add_f32_e32 v229, v230, v229
	v_exp_f32_e32 v210, v94
	v_exp_f32_e32 v226, v78
	v_add_f32_e32 v228, v224, v208
	v_add_f32_e32 v229, v228, v229
	v_exp_f32_e32 v211, v95
	v_exp_f32_e32 v227, v79
	v_add_f32_e32 v230, v225, v209
	v_add_f32_e32 v229, v230, v229
	v_add_f32_e32 v228, v226, v210
	v_add_f32_e32 v229, v228, v229
	v_add_f32_e32 v230, v227, v211
	v_add_f32_e32 v231, v230, v229
	v_cmp_lt_f32_e32 vcc, 0x46000000, v231
	s_cbranch_vccnz .Lat_slow
	v_cvt_pk_bf16_f32 v64, v196, v197
	v_cvt_pk_bf16_f32 v65, v198, v199
	v_cvt_pk_bf16_f32 v66, v200, v201
	v_cvt_pk_bf16_f32 v67, v202, v203
	v_cvt_pk_bf16_f32 v68, v204, v205
	v_cvt_pk_bf16_f32 v69, v206, v207
	v_cvt_pk_bf16_f32 v70, v208, v209
	v_cvt_pk_bf16_f32 v71, v210, v211
	v_cvt_pk_bf16_f32 v72, v212, v213
	v_cvt_pk_bf16_f32 v73, v214, v215
	v_cvt_pk_bf16_f32 v74, v216, v217
	v_cvt_pk_bf16_f32 v75, v218, v219
	v_cvt_pk_bf16_f32 v76, v220, v221
	v_cvt_pk_bf16_f32 v77, v222, v223
	v_cvt_pk_bf16_f32 v78, v224, v225
	v_cvt_pk_bf16_f32 v79, v226, v227
	v_add_f32_e32 v159, v159, v231
	s_waitcnt lgkmcnt(0)
	s_setprio 2
	v_mfma_f32_32x32x16_bf16 v[32:47], v[148:151], v[64:67], v[32:47]
	v_mfma_f32_32x32x16_bf16 v[16:31], v[132:135], v[64:67], v[16:31]
	v_mfma_f32_32x32x16_bf16 v[32:47], v[144:147], v[68:71], v[32:47]
	v_mfma_f32_32x32x16_bf16 v[16:31], v[128:131], v[68:71], v[16:31]
	v_mfma_f32_32x32x16_bf16 v[32:47], v[140:143], v[72:75], v[32:47]
	v_mfma_f32_32x32x16_bf16 v[16:31], v[10:13], v[72:75], v[16:31]
	v_mfma_f32_32x32x16_bf16 v[32:47], v[136:139], v[76:79], v[32:47]
	v_mfma_f32_32x32x16_bf16 v[16:31], v[6:9], v[76:79], v[16:31]
	s_setprio 0
